# FFN-up gemm8: transposed accumulators (MFMA A/B swapped) + rewritten epilogue (rcp-based silu, permlane16_swap, dwordx4 stores)
# speedup vs baseline: 1.0245x; 1.0154x over previous
.LBB0_1146:
	ds_read_b128 v[160:163], v196
	ds_read_b128 v[164:167], v197
	ds_read_b128 v[180:183], v197 offset:64
	ds_read_b128 v[168:171], v196 offset:64
	ds_read_b128 v[172:175], v197 offset:2304
	ds_read_b128 v[206:209], v197 offset:2368
	ds_read_b128 v[176:179], v197 offset:4608
	ds_read_b128 v[210:213], v197 offset:4672
	ds_read_b128 v[184:187], v197 offset:6912
	ds_read_b128 v[214:217], v197 offset:6976
	s_waitcnt lgkmcnt(8)
	v_mfma_f32_16x16x32_bf16 v[156:159], v[164:167], v[160:163], v[156:159]
	s_add_i32 s41, s41, 2
	s_add_u32 s42, s39, 0xffffff80
	s_addc_u32 s43, s40, -1
	s_waitcnt lgkmcnt(5)
	v_mfma_f32_16x16x32_bf16 v[152:155], v[172:175], v[160:163], v[152:155]
	s_add_u32 s44, s26, 0xffffff80
	s_addc_u32 s45, s27, -1
	s_cmp_gt_u32 s41, 13
	s_waitcnt lgkmcnt(3)
	v_mfma_f32_16x16x32_bf16 v[148:151], v[176:179], v[160:163], v[148:151]
	s_cselect_b64 s[4:5], -1, 0
	s_and_b64 vcc, s[4:5], exec
	s_cselect_b32 s5, s11, s43
	s_waitcnt lgkmcnt(1)
	v_mfma_f32_16x16x32_bf16 v[144:147], v[184:187], v[160:163], v[144:147]
	ds_read_b128 v[160:163], v196 offset:2304
	ds_read_b128 v[188:191], v196 offset:2368
	s_cselect_b32 s4, s10, s42
	s_cselect_b32 s43, s13, s45
	s_waitcnt lgkmcnt(1)
	v_mfma_f32_16x16x32_bf16 v[140:143], v[164:167], v[160:163], v[140:143]
	s_cselect_b32 s42, s12, s44
	s_cmp_gt_u32 s41, 12
	v_mfma_f32_16x16x32_bf16 v[136:139], v[172:175], v[160:163], v[136:139]
	v_mfma_f32_16x16x32_bf16 v[132:135], v[176:179], v[160:163], v[132:135]
	v_mfma_f32_16x16x32_bf16 v[128:131], v[184:187], v[160:163], v[128:131]
	ds_read_b128 v[160:163], v196 offset:4608
	ds_read_b128 v[218:221], v196 offset:4672
	s_waitcnt lgkmcnt(1)
	v_mfma_f32_16x16x32_bf16 v[124:127], v[164:167], v[160:163], v[124:127]
	v_mfma_f32_16x16x32_bf16 v[120:123], v[172:175], v[160:163], v[120:123]
	v_mfma_f32_16x16x32_bf16 v[116:119], v[176:179], v[160:163], v[116:119]
	v_mfma_f32_16x16x32_bf16 v[112:115], v[184:187], v[160:163], v[112:115]
	ds_read_b128 v[160:163], v196 offset:6912
	ds_read_b128 v[222:225], v196 offset:6976
	s_waitcnt lgkmcnt(1)
	v_mfma_f32_16x16x32_bf16 v[108:111], v[164:167], v[160:163], v[108:111]
	v_mfma_f32_16x16x32_bf16 v[104:107], v[172:175], v[160:163], v[104:107]
	v_mfma_f32_16x16x32_bf16 v[100:103], v[176:179], v[160:163], v[100:103]
	v_mfma_f32_16x16x32_bf16 v[96:99], v[184:187], v[160:163], v[96:99]
	ds_read_b128 v[160:163], v196 offset:9216
	ds_read_b128 v[226:229], v196 offset:9280
	s_waitcnt lgkmcnt(1)
	v_mfma_f32_16x16x32_bf16 v[92:95], v[164:167], v[160:163], v[92:95]
	v_mfma_f32_16x16x32_bf16 v[88:91], v[172:175], v[160:163], v[88:91]
	v_mfma_f32_16x16x32_bf16 v[84:87], v[176:179], v[160:163], v[84:87]
	v_mfma_f32_16x16x32_bf16 v[80:83], v[184:187], v[160:163], v[80:83]
	ds_read_b128 v[160:163], v196 offset:11520
	ds_read_b128 v[230:233], v196 offset:11584
	s_waitcnt lgkmcnt(1)
	v_mfma_f32_16x16x32_bf16 v[76:79], v[164:167], v[160:163], v[76:79]
	v_mfma_f32_16x16x32_bf16 v[72:75], v[172:175], v[160:163], v[72:75]
	v_mfma_f32_16x16x32_bf16 v[68:71], v[176:179], v[160:163], v[68:71]
	v_mfma_f32_16x16x32_bf16 v[64:67], v[184:187], v[160:163], v[64:67]
	ds_read_b128 v[160:163], v196 offset:13824
	ds_read_b128 v[234:237], v196 offset:13888
	s_waitcnt lgkmcnt(1)
	v_mfma_f32_16x16x32_bf16 v[60:63], v[164:167], v[160:163], v[60:63]
	v_mfma_f32_16x16x32_bf16 v[56:59], v[172:175], v[160:163], v[56:59]
	v_mfma_f32_16x16x32_bf16 v[52:55], v[176:179], v[160:163], v[52:55]
	v_mfma_f32_16x16x32_bf16 v[48:51], v[184:187], v[160:163], v[48:51]
	ds_read_b128 v[160:163], v196 offset:16128
	ds_read_b128 v[238:241], v196 offset:16192
	s_waitcnt vmcnt(6)
	ds_write_b128 v194, v[4:7] offset:36864
	s_waitcnt vmcnt(5)
	ds_write_b128 v194, v[8:11] offset:46080
	s_waitcnt vmcnt(4)
	ds_write_b128 v194, v[12:15] offset:55296
	s_waitcnt vmcnt(3)
	ds_write_b128 v194, v[16:19] offset:64512
	s_waitcnt vmcnt(3)
	ds_write_b128 v199, v[0:3]
	s_waitcnt vmcnt(2)
	ds_write_b128 v199, v[20:23] offset:9216
	v_mfma_f32_16x16x32_bf16 v[20:23], v[214:217], v[226:229], v[80:83]
	s_waitcnt vmcnt(1)
	ds_write_b128 v199, v[24:27] offset:18432
	s_waitcnt vmcnt(0)
	ds_write_b128 v199, v[28:31] offset:27648
	v_lshl_add_u64 v[80:81], s[4:5], 0, v[192:193]
	v_mfma_f32_16x16x32_bf16 v[24:27], v[180:183], v[230:233], v[76:79]
	v_lshl_add_u64 v[82:83], s[42:43], 0, v[192:193]
	s_cselect_b32 s43, s38, s27
	s_cselect_b32 s42, s37, s26
	v_add_co_u32_e64 v76, s[4:5], s23, v80
	v_mfma_f32_16x16x32_bf16 v[28:31], v[206:209], v[230:233], v[72:75]
	s_nop 0
	v_addc_co_u32_e64 v77, s[4:5], 0, v81, s[4:5]
	s_nop 0
	v_add_co_u32_e64 v72, s[4:5], s25, v80
	s_waitcnt lgkmcnt(9)
	v_mfma_f32_16x16x32_bf16 v[36:39], v[164:167], v[160:163], v[36:39]
	v_addc_co_u32_e64 v73, s[4:5], 0, v81, s[4:5]
	v_add_co_u32_e64 v74, s[4:5], s30, v80
	v_mfma_f32_16x16x32_bf16 v[32:35], v[172:175], v[160:163], v[32:35]
	s_nop 0
	v_addc_co_u32_e64 v75, s[4:5], 0, v81, s[4:5]
	v_add_co_u32_e64 v78, s[4:5], s23, v82
	v_mfma_f32_16x16x32_bf16 v[44:47], v[176:179], v[160:163], v[44:47]
	s_nop 0
	v_addc_co_u32_e64 v79, s[4:5], 0, v83, s[4:5]
	global_load_dwordx4 v[164:167], v[82:83], off
	v_mfma_f32_16x16x32_bf16 v[40:43], v[184:187], v[160:163], v[40:43]
	global_load_dwordx4 v[160:163], v[80:81], off
	v_add_co_u32_e64 v80, s[4:5], s25, v82
	v_mfma_f32_16x16x32_bf16 v[156:159], v[180:183], v[168:171], v[156:159]
	s_nop 0
	v_addc_co_u32_e64 v81, s[4:5], 0, v83, s[4:5]
	v_add_co_u32_e64 v82, s[4:5], s30, v82
	v_mfma_f32_16x16x32_bf16 v[152:155], v[206:209], v[168:171], v[152:155]
	s_nop 0
	v_addc_co_u32_e64 v83, s[4:5], 0, v83, s[4:5]
	s_cselect_b32 s5, s21, s40
	v_mfma_f32_16x16x32_bf16 v[148:151], v[210:213], v[168:171], v[148:151]
	s_cselect_b32 s4, s19, s39
	s_add_u32 s26, s26, 0x100
	s_addc_u32 s27, s27, 0
	v_mfma_f32_16x16x32_bf16 v[144:147], v[214:217], v[168:171], v[144:147]
	global_load_dwordx4 v[168:171], v[76:77], off
	global_load_dwordx4 v[172:175], v[72:73], off
	global_load_dwordx4 v[176:179], v[74:75], off
	s_add_u32 s39, s39, 0x100
	s_addc_u32 s40, s40, 0
	v_mfma_f32_16x16x32_bf16 v[140:143], v[180:183], v[188:191], v[140:143]
	v_mfma_f32_16x16x32_bf16 v[136:139], v[206:209], v[188:191], v[136:139]
	v_mfma_f32_16x16x32_bf16 v[132:135], v[210:213], v[188:191], v[132:135]
	v_mfma_f32_16x16x32_bf16 v[128:131], v[214:217], v[188:191], v[128:131]
	v_mfma_f32_16x16x32_bf16 v[124:127], v[180:183], v[218:221], v[124:127]
	v_mfma_f32_16x16x32_bf16 v[108:111], v[180:183], v[222:225], v[108:111]
	v_mfma_f32_16x16x32_bf16 v[8:11], v[180:183], v[226:229], v[92:95]
	v_mfma_f32_16x16x32_bf16 v[60:63], v[180:183], v[234:237], v[60:63]
	s_waitcnt lgkmcnt(8)
	v_mfma_f32_16x16x32_bf16 v[36:39], v[180:183], v[238:241], v[36:39]
	global_load_dwordx4 v[180:183], v[78:79], off
	global_load_dwordx4 v[184:187], v[80:81], off
	global_load_dwordx4 v[188:191], v[82:83], off
	s_waitcnt lgkmcnt(0)
	s_barrier
	ds_read_b128 v[76:79], v196 offset:36864
	v_mfma_f32_16x16x32_bf16 v[120:123], v[206:209], v[218:221], v[120:123]
	v_mfma_f32_16x16x32_bf16 v[116:119], v[210:213], v[218:221], v[116:119]
	v_mfma_f32_16x16x32_bf16 v[104:107], v[206:209], v[222:225], v[104:107]
	v_mfma_f32_16x16x32_bf16 v[4:7], v[210:213], v[222:225], v[100:103]
	v_mfma_f32_16x16x32_bf16 v[0:3], v[214:217], v[222:225], v[96:99]
	v_mfma_f32_16x16x32_bf16 v[12:15], v[206:209], v[226:229], v[88:91]
	v_mfma_f32_16x16x32_bf16 v[16:19], v[210:213], v[226:229], v[84:87]
	v_mfma_f32_16x16x32_bf16 v[68:71], v[210:213], v[230:233], v[68:71]
	v_mfma_f32_16x16x32_bf16 v[56:59], v[206:209], v[234:237], v[56:59]
	v_mfma_f32_16x16x32_bf16 v[52:55], v[210:213], v[234:237], v[52:55]
	v_mfma_f32_16x16x32_bf16 v[32:35], v[206:209], v[238:241], v[32:35]
	ds_read_b128 v[84:87], v200
	ds_read_b128 v[206:209], v200 offset:64
	ds_read_b128 v[88:91], v196 offset:36928
	v_mfma_f32_16x16x32_bf16 v[72:75], v[210:213], v[238:241], v[44:47]
	ds_read_b128 v[96:99], v200 offset:2304
	ds_read_b128 v[210:213], v200 offset:2368
	v_mfma_f32_16x16x32_bf16 v[80:83], v[214:217], v[238:241], v[40:43]
	s_waitcnt lgkmcnt(4)
	v_mfma_f32_16x16x32_bf16 v[92:95], v[84:87], v[76:79], v[156:159]
	s_waitcnt lgkmcnt(1)
	v_mfma_f32_16x16x32_bf16 v[100:103], v[96:99], v[76:79], v[152:155]
	s_nop 2
	ds_read_b128 v[152:155], v200 offset:4608
	ds_read_b128 v[44:47], v200 offset:4672
	ds_read_b128 v[156:159], v200 offset:6912
	ds_read_b128 v[40:43], v200 offset:6976
	v_mfma_f32_16x16x32_bf16 v[112:115], v[214:217], v[218:221], v[112:115]
	v_mfma_f32_16x16x32_bf16 v[64:67], v[214:217], v[230:233], v[64:67]
	v_mfma_f32_16x16x32_bf16 v[48:51], v[214:217], v[234:237], v[48:51]
	s_waitcnt lgkmcnt(3)
	v_mfma_f32_16x16x32_bf16 v[148:151], v[152:155], v[76:79], v[148:151]
	s_waitcnt lgkmcnt(1)
	v_mfma_f32_16x16x32_bf16 v[76:79], v[156:159], v[76:79], v[144:147]
	s_nop 2
	ds_read_b128 v[144:147], v196 offset:39168
	ds_read_b128 v[214:217], v196 offset:39232
	s_waitcnt lgkmcnt(1)
	v_mfma_f32_16x16x32_bf16 v[140:143], v[84:87], v[144:147], v[140:143]
	v_mfma_f32_16x16x32_bf16 v[136:139], v[96:99], v[144:147], v[136:139]
	v_mfma_f32_16x16x32_bf16 v[132:135], v[152:155], v[144:147], v[132:135]
	v_mfma_f32_16x16x32_bf16 v[128:131], v[156:159], v[144:147], v[128:131]
	ds_read_b128 v[144:147], v196 offset:41472
	ds_read_b128 v[218:221], v196 offset:41536
	s_waitcnt lgkmcnt(1)
	v_mfma_f32_16x16x32_bf16 v[124:127], v[84:87], v[144:147], v[124:127]
	v_mfma_f32_16x16x32_bf16 v[120:123], v[96:99], v[144:147], v[120:123]
	v_mfma_f32_16x16x32_bf16 v[116:119], v[152:155], v[144:147], v[116:119]
	v_mfma_f32_16x16x32_bf16 v[112:115], v[156:159], v[144:147], v[112:115]
	ds_read_b128 v[144:147], v196 offset:43776
	ds_read_b128 v[222:225], v196 offset:43840
	s_waitcnt lgkmcnt(1)
	v_mfma_f32_16x16x32_bf16 v[108:111], v[84:87], v[144:147], v[108:111]
	v_mfma_f32_16x16x32_bf16 v[104:107], v[96:99], v[144:147], v[104:107]
	v_mfma_f32_16x16x32_bf16 v[4:7], v[152:155], v[144:147], v[4:7]
	v_mfma_f32_16x16x32_bf16 v[0:3], v[156:159], v[144:147], v[0:3]
	ds_read_b128 v[144:147], v196 offset:46080
	ds_read_b128 v[226:229], v196 offset:46144
	s_waitcnt lgkmcnt(1)
	v_mfma_f32_16x16x32_bf16 v[8:11], v[84:87], v[144:147], v[8:11]
	v_mfma_f32_16x16x32_bf16 v[12:15], v[96:99], v[144:147], v[12:15]
	v_mfma_f32_16x16x32_bf16 v[16:19], v[152:155], v[144:147], v[16:19]
	v_mfma_f32_16x16x32_bf16 v[20:23], v[156:159], v[144:147], v[20:23]
	ds_read_b128 v[144:147], v196 offset:48384
	ds_read_b128 v[230:233], v196 offset:48448
	s_waitcnt lgkmcnt(1)
	v_mfma_f32_16x16x32_bf16 v[24:27], v[84:87], v[144:147], v[24:27]
	v_mfma_f32_16x16x32_bf16 v[28:31], v[96:99], v[144:147], v[28:31]
	v_mfma_f32_16x16x32_bf16 v[68:71], v[152:155], v[144:147], v[68:71]
	v_mfma_f32_16x16x32_bf16 v[64:67], v[156:159], v[144:147], v[64:67]
	ds_read_b128 v[144:147], v196 offset:50688
	ds_read_b128 v[234:237], v196 offset:50752
	s_waitcnt lgkmcnt(1)
	v_mfma_f32_16x16x32_bf16 v[60:63], v[84:87], v[144:147], v[60:63]
	v_mfma_f32_16x16x32_bf16 v[56:59], v[96:99], v[144:147], v[56:59]
	v_mfma_f32_16x16x32_bf16 v[52:55], v[152:155], v[144:147], v[52:55]
	v_mfma_f32_16x16x32_bf16 v[48:51], v[156:159], v[144:147], v[48:51]
	ds_read_b128 v[144:147], v196 offset:52992
	ds_read_b128 v[238:241], v196 offset:53056
	s_waitcnt lgkmcnt(1)
	v_mfma_f32_16x16x32_bf16 v[242:245], v[152:155], v[144:147], v[72:75]
	v_mfma_f32_16x16x32_bf16 v[152:155], v[210:213], v[88:91], v[100:103]
	v_mfma_f32_16x16x32_bf16 v[100:103], v[44:47], v[222:225], v[4:7]
	s_nop 2
	v_lshl_add_u64 v[4:5], s[4:5], 0, v[192:193]
	v_mfma_f32_16x16x32_bf16 v[246:249], v[156:159], v[144:147], v[80:83]
	v_lshl_add_u64 v[6:7], s[42:43], 0, v[192:193]
	v_mfma_f32_16x16x32_bf16 v[156:159], v[206:209], v[88:91], v[92:95]
	v_mfma_f32_16x16x32_bf16 v[92:95], v[206:209], v[226:229], v[8:11]
	s_nop 2
	v_add_co_u32_e64 v8, s[4:5], s23, v4
	v_mfma_f32_16x16x32_bf16 v[36:39], v[84:87], v[144:147], v[36:39]
	s_nop 0
	v_addc_co_u32_e64 v9, s[4:5], 0, v5, s[4:5]
	v_mfma_f32_16x16x32_bf16 v[32:35], v[96:99], v[144:147], v[32:35]
	v_mfma_f32_16x16x32_bf16 v[148:151], v[44:47], v[88:91], v[148:151]
	v_mfma_f32_16x16x32_bf16 v[144:147], v[40:43], v[88:91], v[76:79]
	v_mfma_f32_16x16x32_bf16 v[88:91], v[210:213], v[226:229], v[12:15]
	s_nop 2
	v_add_co_u32_e64 v12, s[4:5], s25, v4
	v_mfma_f32_16x16x32_bf16 v[84:87], v[44:47], v[226:229], v[16:19]
	s_nop 0
	v_addc_co_u32_e64 v13, s[4:5], 0, v5, s[4:5]
	s_nop 0
	v_add_co_u32_e64 v16, s[4:5], s30, v4
	v_mfma_f32_16x16x32_bf16 v[80:83], v[40:43], v[226:229], v[20:23]
	s_nop 0
	v_addc_co_u32_e64 v17, s[4:5], 0, v5, s[4:5]
	s_nop 0
	v_add_co_u32_e64 v20, s[4:5], s23, v6
	v_mfma_f32_16x16x32_bf16 v[76:79], v[206:209], v[230:233], v[24:27]
	s_nop 0
	v_addc_co_u32_e64 v21, s[4:5], 0, v7, s[4:5]
	s_nop 0
	v_add_co_u32_e64 v24, s[4:5], s25, v6
	v_mfma_f32_16x16x32_bf16 v[72:75], v[210:213], v[230:233], v[28:31]
	s_nop 0
	v_addc_co_u32_e64 v25, s[4:5], 0, v7, s[4:5]
	s_nop 0
	v_add_co_u32_e64 v28, s[4:5], s30, v6
	v_mfma_f32_16x16x32_bf16 v[96:99], v[40:43], v[222:225], v[0:3]
	s_nop 0
	v_addc_co_u32_e64 v29, s[4:5], 0, v7, s[4:5]
	s_nop 0
	global_load_dwordx4 v[0:3], v[6:7], off
	s_nop 0
	global_load_dwordx4 v[4:7], v[4:5], off
	s_nop 0
	global_load_dwordx4 v[8:11], v[8:9], off
	s_nop 0
	global_load_dwordx4 v[12:15], v[12:13], off
	s_nop 0
	global_load_dwordx4 v[16:19], v[16:17], off
	s_nop 0
	global_load_dwordx4 v[20:23], v[20:21], off
	s_nop 0
	global_load_dwordx4 v[24:27], v[24:25], off
	v_mfma_f32_16x16x32_bf16 v[140:143], v[206:209], v[214:217], v[140:143]
	global_load_dwordx4 v[28:31], v[28:29], off
	s_waitcnt vmcnt(14)
	ds_write_b128 v194, v[160:163]
	ds_write_b128 v195, v[164:167]
	s_waitcnt vmcnt(13)
	ds_write_b128 v194, v[168:171] offset:9216
	s_waitcnt vmcnt(12)
	ds_write_b128 v194, v[172:175] offset:18432
	s_waitcnt vmcnt(11)
	ds_write_b128 v194, v[176:179] offset:27648
	s_waitcnt vmcnt(10)
	ds_write_b128 v195, v[180:183] offset:9216
	s_waitcnt vmcnt(9)
	ds_write_b128 v195, v[184:187] offset:18432
	s_waitcnt vmcnt(8)
	ds_write_b128 v195, v[188:191] offset:27648
	s_waitcnt lgkmcnt(0)
	v_mfma_f32_16x16x32_bf16 v[136:139], v[210:213], v[214:217], v[136:139]
	s_barrier
	v_mfma_f32_16x16x32_bf16 v[132:135], v[44:47], v[214:217], v[132:135]
	v_mfma_f32_16x16x32_bf16 v[128:131], v[40:43], v[214:217], v[128:131]
	v_mfma_f32_16x16x32_bf16 v[124:127], v[206:209], v[218:221], v[124:127]
	v_mfma_f32_16x16x32_bf16 v[120:123], v[210:213], v[218:221], v[120:123]
	v_mfma_f32_16x16x32_bf16 v[116:119], v[44:47], v[218:221], v[116:119]
	v_mfma_f32_16x16x32_bf16 v[112:115], v[40:43], v[218:221], v[112:115]
	v_mfma_f32_16x16x32_bf16 v[108:111], v[206:209], v[222:225], v[108:111]
	v_mfma_f32_16x16x32_bf16 v[104:107], v[210:213], v[222:225], v[104:107]
	v_mfma_f32_16x16x32_bf16 v[68:71], v[44:47], v[230:233], v[68:71]
	v_mfma_f32_16x16x32_bf16 v[64:67], v[40:43], v[230:233], v[64:67]
	v_mfma_f32_16x16x32_bf16 v[60:63], v[206:209], v[234:237], v[60:63]
	v_mfma_f32_16x16x32_bf16 v[56:59], v[210:213], v[234:237], v[56:59]
	v_mfma_f32_16x16x32_bf16 v[52:55], v[44:47], v[234:237], v[52:55]
	v_mfma_f32_16x16x32_bf16 v[48:51], v[40:43], v[234:237], v[48:51]
	v_mfma_f32_16x16x32_bf16 v[36:39], v[206:209], v[238:241], v[36:39]
	v_mfma_f32_16x16x32_bf16 v[32:35], v[210:213], v[238:241], v[32:35]
	v_mfma_f32_16x16x32_bf16 v[44:47], v[44:47], v[238:241], v[242:245]
	v_mfma_f32_16x16x32_bf16 v[40:43], v[40:43], v[238:241], v[246:249]
	s_cbranch_vccz .LBB0_1146
	s_mul_i32 s98, s22, 0x1600
	s_add_u32 s98, s98, s24
	s_add_u32 s100, s8, s98
	s_addc_u32 s101, s9, 0
	v_and_b32_e32 v168, 15, v198
	v_and_b32_e32 v169, 0x80, v201
	v_add_u32_e32 v168, v168, v169
	v_mul_u32_u24_e32 v168, 0x1600, v168
	v_and_b32_e32 v169, 0xc0, v198
	v_add_u32_e32 v168, v168, v169
	v_and_b32_e32 v169, 4, v201
	v_lshl_add_u32 v168, v169, 3, v168
	v_and_b32_e32 v169, 8, v201
	v_lshl_add_u32 v168, v169, 1, v168
	v_mul_f32_e32 v160, 0xbfb8aa3b, v156
	v_mul_f32_e32 v161, 0xbfb8aa3b, v157
	v_mul_f32_e32 v162, 0xbfb8aa3b, v158
	v_mul_f32_e32 v163, 0xbfb8aa3b, v159
	v_mul_f32_e32 v164, 0xbfb8aa3b, v148
	v_mul_f32_e32 v165, 0xbfb8aa3b, v149
	v_mul_f32_e32 v166, 0xbfb8aa3b, v150
	v_mul_f32_e32 v167, 0xbfb8aa3b, v151
	v_exp_f32_e32 v160, v160
	v_exp_f32_e32 v161, v161
	v_exp_f32_e32 v162, v162
	v_exp_f32_e32 v163, v163
	v_exp_f32_e32 v164, v164
	v_exp_f32_e32 v165, v165
	v_exp_f32_e32 v166, v166
	v_exp_f32_e32 v167, v167
	v_add_f32_e32 v160, 1.0, v160
	v_add_f32_e32 v161, 1.0, v161
	v_add_f32_e32 v162, 1.0, v162
	v_add_f32_e32 v163, 1.0, v163
	v_add_f32_e32 v164, 1.0, v164
	v_add_f32_e32 v165, 1.0, v165
	v_add_f32_e32 v166, 1.0, v166
	v_add_f32_e32 v167, 1.0, v167
	v_rcp_f32_e32 v160, v160
	v_rcp_f32_e32 v161, v161
	v_rcp_f32_e32 v162, v162
	v_rcp_f32_e32 v163, v163
	v_rcp_f32_e32 v164, v164
	v_rcp_f32_e32 v165, v165
	v_rcp_f32_e32 v166, v166
	v_rcp_f32_e32 v167, v167
	v_mul_f32_e32 v156, v156, v160
	v_mul_f32_e32 v157, v157, v161
	v_mul_f32_e32 v158, v158, v162
	v_mul_f32_e32 v159, v159, v163
	v_mul_f32_e32 v148, v148, v164
	v_mul_f32_e32 v149, v149, v165
	v_mul_f32_e32 v150, v150, v166
	v_mul_f32_e32 v151, v151, v167
	v_mul_f32_e32 v152, v156, v152
	v_mul_f32_e32 v153, v157, v153
	v_mul_f32_e32 v154, v158, v154
	v_mul_f32_e32 v155, v159, v155
	v_mul_f32_e32 v144, v148, v144
	v_mul_f32_e32 v145, v149, v145
	v_mul_f32_e32 v146, v150, v146
	v_mul_f32_e32 v147, v151, v147
	v_cvt_pk_bf16_f32 v156, v152, v153
	v_cvt_pk_bf16_f32 v157, v154, v155
	v_cvt_pk_bf16_f32 v158, v144, v145
	v_cvt_pk_bf16_f32 v159, v146, v147
	s_nop 1
	v_permlane16_swap_b32_e32 v156, v158
	v_permlane16_swap_b32_e32 v157, v159
	global_store_dwordx4 v168, v[156:159], s[100:101]
	s_add_u32 s100, s100, 0x16000
	s_addc_u32 s101, s101, 0
	v_mul_f32_e32 v160, 0xbfb8aa3b, v140
	v_mul_f32_e32 v161, 0xbfb8aa3b, v141
	v_mul_f32_e32 v162, 0xbfb8aa3b, v142
	v_mul_f32_e32 v163, 0xbfb8aa3b, v143
	v_mul_f32_e32 v164, 0xbfb8aa3b, v132
	v_mul_f32_e32 v165, 0xbfb8aa3b, v133
	v_mul_f32_e32 v166, 0xbfb8aa3b, v134
	v_mul_f32_e32 v167, 0xbfb8aa3b, v135
	v_exp_f32_e32 v160, v160
	v_exp_f32_e32 v161, v161
	v_exp_f32_e32 v162, v162
	v_exp_f32_e32 v163, v163
	v_exp_f32_e32 v164, v164
	v_exp_f32_e32 v165, v165
	v_exp_f32_e32 v166, v166
	v_exp_f32_e32 v167, v167
	v_add_f32_e32 v160, 1.0, v160
	v_add_f32_e32 v161, 1.0, v161
	v_add_f32_e32 v162, 1.0, v162
	v_add_f32_e32 v163, 1.0, v163
	v_add_f32_e32 v164, 1.0, v164
	v_add_f32_e32 v165, 1.0, v165
	v_add_f32_e32 v166, 1.0, v166
	v_add_f32_e32 v167, 1.0, v167
	v_rcp_f32_e32 v160, v160
	v_rcp_f32_e32 v161, v161
	v_rcp_f32_e32 v162, v162
	v_rcp_f32_e32 v163, v163
	v_rcp_f32_e32 v164, v164
	v_rcp_f32_e32 v165, v165
	v_rcp_f32_e32 v166, v166
	v_rcp_f32_e32 v167, v167
	v_mul_f32_e32 v140, v140, v160
	v_mul_f32_e32 v141, v141, v161
	v_mul_f32_e32 v142, v142, v162
	v_mul_f32_e32 v143, v143, v163
	v_mul_f32_e32 v132, v132, v164
	v_mul_f32_e32 v133, v133, v165
	v_mul_f32_e32 v134, v134, v166
	v_mul_f32_e32 v135, v135, v167
	v_mul_f32_e32 v136, v140, v136
	v_mul_f32_e32 v137, v141, v137
	v_mul_f32_e32 v138, v142, v138
	v_mul_f32_e32 v139, v143, v139
	v_mul_f32_e32 v128, v132, v128
	v_mul_f32_e32 v129, v133, v129
	v_mul_f32_e32 v130, v134, v130
	v_mul_f32_e32 v131, v135, v131
	v_cvt_pk_bf16_f32 v140, v136, v137
	v_cvt_pk_bf16_f32 v141, v138, v139
	v_cvt_pk_bf16_f32 v142, v128, v129
	v_cvt_pk_bf16_f32 v143, v130, v131
	s_nop 1
	v_permlane16_swap_b32_e32 v140, v142
	v_permlane16_swap_b32_e32 v141, v143
	global_store_dwordx4 v168, v[140:143], s[100:101]
	s_add_u32 s100, s100, 0x16000
	s_addc_u32 s101, s101, 0
	v_mul_f32_e32 v160, 0xbfb8aa3b, v124
	v_mul_f32_e32 v161, 0xbfb8aa3b, v125
	v_mul_f32_e32 v162, 0xbfb8aa3b, v126
	v_mul_f32_e32 v163, 0xbfb8aa3b, v127
	v_mul_f32_e32 v164, 0xbfb8aa3b, v116
	v_mul_f32_e32 v165, 0xbfb8aa3b, v117
	v_mul_f32_e32 v166, 0xbfb8aa3b, v118
	v_mul_f32_e32 v167, 0xbfb8aa3b, v119
	v_exp_f32_e32 v160, v160
	v_exp_f32_e32 v161, v161
	v_exp_f32_e32 v162, v162
	v_exp_f32_e32 v163, v163
	v_exp_f32_e32 v164, v164
	v_exp_f32_e32 v165, v165
	v_exp_f32_e32 v166, v166
	v_exp_f32_e32 v167, v167
	v_add_f32_e32 v160, 1.0, v160
	v_add_f32_e32 v161, 1.0, v161
	v_add_f32_e32 v162, 1.0, v162
	v_add_f32_e32 v163, 1.0, v163
	v_add_f32_e32 v164, 1.0, v164
	v_add_f32_e32 v165, 1.0, v165
	v_add_f32_e32 v166, 1.0, v166
	v_add_f32_e32 v167, 1.0, v167
	v_rcp_f32_e32 v160, v160
	v_rcp_f32_e32 v161, v161
	v_rcp_f32_e32 v162, v162
	v_rcp_f32_e32 v163, v163
	v_rcp_f32_e32 v164, v164
	v_rcp_f32_e32 v165, v165
	v_rcp_f32_e32 v166, v166
	v_rcp_f32_e32 v167, v167
	v_mul_f32_e32 v124, v124, v160
	v_mul_f32_e32 v125, v125, v161
	v_mul_f32_e32 v126, v126, v162
	v_mul_f32_e32 v127, v127, v163
	v_mul_f32_e32 v116, v116, v164
	v_mul_f32_e32 v117, v117, v165
	v_mul_f32_e32 v118, v118, v166
	v_mul_f32_e32 v119, v119, v167
	v_mul_f32_e32 v120, v124, v120
	v_mul_f32_e32 v121, v125, v121
	v_mul_f32_e32 v122, v126, v122
	v_mul_f32_e32 v123, v127, v123
	v_mul_f32_e32 v112, v116, v112
	v_mul_f32_e32 v113, v117, v113
	v_mul_f32_e32 v114, v118, v114
	v_mul_f32_e32 v115, v119, v115
	v_cvt_pk_bf16_f32 v124, v120, v121
	v_cvt_pk_bf16_f32 v125, v122, v123
	v_cvt_pk_bf16_f32 v126, v112, v113
	v_cvt_pk_bf16_f32 v127, v114, v115
	s_nop 1
	v_permlane16_swap_b32_e32 v124, v126
	v_permlane16_swap_b32_e32 v125, v127
	global_store_dwordx4 v168, v[124:127], s[100:101]
	s_add_u32 s100, s100, 0x16000
	s_addc_u32 s101, s101, 0
	v_mul_f32_e32 v160, 0xbfb8aa3b, v108
	v_mul_f32_e32 v161, 0xbfb8aa3b, v109
	v_mul_f32_e32 v162, 0xbfb8aa3b, v110
	v_mul_f32_e32 v163, 0xbfb8aa3b, v111
	v_mul_f32_e32 v164, 0xbfb8aa3b, v100
	v_mul_f32_e32 v165, 0xbfb8aa3b, v101
	v_mul_f32_e32 v166, 0xbfb8aa3b, v102
	v_mul_f32_e32 v167, 0xbfb8aa3b, v103
	v_exp_f32_e32 v160, v160
	v_exp_f32_e32 v161, v161
	v_exp_f32_e32 v162, v162
	v_exp_f32_e32 v163, v163
	v_exp_f32_e32 v164, v164
	v_exp_f32_e32 v165, v165
	v_exp_f32_e32 v166, v166
	v_exp_f32_e32 v167, v167
	v_add_f32_e32 v160, 1.0, v160
	v_add_f32_e32 v161, 1.0, v161
	v_add_f32_e32 v162, 1.0, v162
	v_add_f32_e32 v163, 1.0, v163
	v_add_f32_e32 v164, 1.0, v164
	v_add_f32_e32 v165, 1.0, v165
	v_add_f32_e32 v166, 1.0, v166
	v_add_f32_e32 v167, 1.0, v167
	v_rcp_f32_e32 v160, v160
	v_rcp_f32_e32 v161, v161
	v_rcp_f32_e32 v162, v162
	v_rcp_f32_e32 v163, v163
	v_rcp_f32_e32 v164, v164
	v_rcp_f32_e32 v165, v165
	v_rcp_f32_e32 v166, v166
	v_rcp_f32_e32 v167, v167
	v_mul_f32_e32 v108, v108, v160
	v_mul_f32_e32 v109, v109, v161
	v_mul_f32_e32 v110, v110, v162
	v_mul_f32_e32 v111, v111, v163
	v_mul_f32_e32 v100, v100, v164
	v_mul_f32_e32 v101, v101, v165
	v_mul_f32_e32 v102, v102, v166
	v_mul_f32_e32 v103, v103, v167
	v_mul_f32_e32 v104, v108, v104
	v_mul_f32_e32 v105, v109, v105
	v_mul_f32_e32 v106, v110, v106
	v_mul_f32_e32 v107, v111, v107
	v_mul_f32_e32 v96, v100, v96
	v_mul_f32_e32 v97, v101, v97
	v_mul_f32_e32 v98, v102, v98
	v_mul_f32_e32 v99, v103, v99
	v_cvt_pk_bf16_f32 v108, v104, v105
	v_cvt_pk_bf16_f32 v109, v106, v107
	v_cvt_pk_bf16_f32 v110, v96, v97
	v_cvt_pk_bf16_f32 v111, v98, v99
	s_nop 1
	v_permlane16_swap_b32_e32 v108, v110
	v_permlane16_swap_b32_e32 v109, v111
	global_store_dwordx4 v168, v[108:111], s[100:101]
	s_add_u32 s100, s100, 0x16000
	s_addc_u32 s101, s101, 0
	v_mul_f32_e32 v160, 0xbfb8aa3b, v92
	v_mul_f32_e32 v161, 0xbfb8aa3b, v93
	v_mul_f32_e32 v162, 0xbfb8aa3b, v94
	v_mul_f32_e32 v163, 0xbfb8aa3b, v95
	v_mul_f32_e32 v164, 0xbfb8aa3b, v84
	v_mul_f32_e32 v165, 0xbfb8aa3b, v85
	v_mul_f32_e32 v166, 0xbfb8aa3b, v86
	v_mul_f32_e32 v167, 0xbfb8aa3b, v87
	v_exp_f32_e32 v160, v160
	v_exp_f32_e32 v161, v161
	v_exp_f32_e32 v162, v162
	v_exp_f32_e32 v163, v163
	v_exp_f32_e32 v164, v164
	v_exp_f32_e32 v165, v165
	v_exp_f32_e32 v166, v166
	v_exp_f32_e32 v167, v167
	v_add_f32_e32 v160, 1.0, v160
	v_add_f32_e32 v161, 1.0, v161
	v_add_f32_e32 v162, 1.0, v162
	v_add_f32_e32 v163, 1.0, v163
	v_add_f32_e32 v164, 1.0, v164
	v_add_f32_e32 v165, 1.0, v165
	v_add_f32_e32 v166, 1.0, v166
	v_add_f32_e32 v167, 1.0, v167
	v_rcp_f32_e32 v160, v160
	v_rcp_f32_e32 v161, v161
	v_rcp_f32_e32 v162, v162
	v_rcp_f32_e32 v163, v163
	v_rcp_f32_e32 v164, v164
	v_rcp_f32_e32 v165, v165
	v_rcp_f32_e32 v166, v166
	v_rcp_f32_e32 v167, v167
	v_mul_f32_e32 v92, v92, v160
	v_mul_f32_e32 v93, v93, v161
	v_mul_f32_e32 v94, v94, v162
	v_mul_f32_e32 v95, v95, v163
	v_mul_f32_e32 v84, v84, v164
	v_mul_f32_e32 v85, v85, v165
	v_mul_f32_e32 v86, v86, v166
	v_mul_f32_e32 v87, v87, v167
	v_mul_f32_e32 v88, v92, v88
	v_mul_f32_e32 v89, v93, v89
	v_mul_f32_e32 v90, v94, v90
	v_mul_f32_e32 v91, v95, v91
	v_mul_f32_e32 v80, v84, v80
	v_mul_f32_e32 v81, v85, v81
	v_mul_f32_e32 v82, v86, v82
	v_mul_f32_e32 v83, v87, v83
	v_cvt_pk_bf16_f32 v92, v88, v89
	v_cvt_pk_bf16_f32 v93, v90, v91
	v_cvt_pk_bf16_f32 v94, v80, v81
	v_cvt_pk_bf16_f32 v95, v82, v83
	s_nop 1
	v_permlane16_swap_b32_e32 v92, v94
	v_permlane16_swap_b32_e32 v93, v95
	global_store_dwordx4 v168, v[92:95], s[100:101]
	s_add_u32 s100, s100, 0x16000
	s_addc_u32 s101, s101, 0
	v_mul_f32_e32 v160, 0xbfb8aa3b, v76
	v_mul_f32_e32 v161, 0xbfb8aa3b, v77
	v_mul_f32_e32 v162, 0xbfb8aa3b, v78
	v_mul_f32_e32 v163, 0xbfb8aa3b, v79
	v_mul_f32_e32 v164, 0xbfb8aa3b, v68
	v_mul_f32_e32 v165, 0xbfb8aa3b, v69
	v_mul_f32_e32 v166, 0xbfb8aa3b, v70
	v_mul_f32_e32 v167, 0xbfb8aa3b, v71
	v_exp_f32_e32 v160, v160
	v_exp_f32_e32 v161, v161
	v_exp_f32_e32 v162, v162
	v_exp_f32_e32 v163, v163
	v_exp_f32_e32 v164, v164
	v_exp_f32_e32 v165, v165
	v_exp_f32_e32 v166, v166
	v_exp_f32_e32 v167, v167
	v_add_f32_e32 v160, 1.0, v160
	v_add_f32_e32 v161, 1.0, v161
	v_add_f32_e32 v162, 1.0, v162
	v_add_f32_e32 v163, 1.0, v163
	v_add_f32_e32 v164, 1.0, v164
	v_add_f32_e32 v165, 1.0, v165
	v_add_f32_e32 v166, 1.0, v166
	v_add_f32_e32 v167, 1.0, v167
	v_rcp_f32_e32 v160, v160
	v_rcp_f32_e32 v161, v161
	v_rcp_f32_e32 v162, v162
	v_rcp_f32_e32 v163, v163
	v_rcp_f32_e32 v164, v164
	v_rcp_f32_e32 v165, v165
	v_rcp_f32_e32 v166, v166
	v_rcp_f32_e32 v167, v167
	v_mul_f32_e32 v76, v76, v160
	v_mul_f32_e32 v77, v77, v161
	v_mul_f32_e32 v78, v78, v162
	v_mul_f32_e32 v79, v79, v163
	v_mul_f32_e32 v68, v68, v164
	v_mul_f32_e32 v69, v69, v165
	v_mul_f32_e32 v70, v70, v166
	v_mul_f32_e32 v71, v71, v167
	v_mul_f32_e32 v72, v76, v72
	v_mul_f32_e32 v73, v77, v73
	v_mul_f32_e32 v74, v78, v74
	v_mul_f32_e32 v75, v79, v75
	v_mul_f32_e32 v64, v68, v64
	v_mul_f32_e32 v65, v69, v65
	v_mul_f32_e32 v66, v70, v66
	v_mul_f32_e32 v67, v71, v67
	v_cvt_pk_bf16_f32 v76, v72, v73
	v_cvt_pk_bf16_f32 v77, v74, v75
	v_cvt_pk_bf16_f32 v78, v64, v65
	v_cvt_pk_bf16_f32 v79, v66, v67
	s_nop 1
	v_permlane16_swap_b32_e32 v76, v78
	v_permlane16_swap_b32_e32 v77, v79
	global_store_dwordx4 v168, v[76:79], s[100:101]
	s_add_u32 s100, s100, 0x16000
	s_addc_u32 s101, s101, 0
	v_mul_f32_e32 v160, 0xbfb8aa3b, v60
	v_mul_f32_e32 v161, 0xbfb8aa3b, v61
	v_mul_f32_e32 v162, 0xbfb8aa3b, v62
	v_mul_f32_e32 v163, 0xbfb8aa3b, v63
	v_mul_f32_e32 v164, 0xbfb8aa3b, v52
	v_mul_f32_e32 v165, 0xbfb8aa3b, v53
	v_mul_f32_e32 v166, 0xbfb8aa3b, v54
	v_mul_f32_e32 v167, 0xbfb8aa3b, v55
	v_exp_f32_e32 v160, v160
	v_exp_f32_e32 v161, v161
	v_exp_f32_e32 v162, v162
	v_exp_f32_e32 v163, v163
	v_exp_f32_e32 v164, v164
	v_exp_f32_e32 v165, v165
	v_exp_f32_e32 v166, v166
	v_exp_f32_e32 v167, v167
	v_add_f32_e32 v160, 1.0, v160
	v_add_f32_e32 v161, 1.0, v161
	v_add_f32_e32 v162, 1.0, v162
	v_add_f32_e32 v163, 1.0, v163
	v_add_f32_e32 v164, 1.0, v164
	v_add_f32_e32 v165, 1.0, v165
	v_add_f32_e32 v166, 1.0, v166
	v_add_f32_e32 v167, 1.0, v167
	v_rcp_f32_e32 v160, v160
	v_rcp_f32_e32 v161, v161
	v_rcp_f32_e32 v162, v162
	v_rcp_f32_e32 v163, v163
	v_rcp_f32_e32 v164, v164
	v_rcp_f32_e32 v165, v165
	v_rcp_f32_e32 v166, v166
	v_rcp_f32_e32 v167, v167
	v_mul_f32_e32 v60, v60, v160
	v_mul_f32_e32 v61, v61, v161
	v_mul_f32_e32 v62, v62, v162
	v_mul_f32_e32 v63, v63, v163
	v_mul_f32_e32 v52, v52, v164
	v_mul_f32_e32 v53, v53, v165
	v_mul_f32_e32 v54, v54, v166
	v_mul_f32_e32 v55, v55, v167
	v_mul_f32_e32 v56, v60, v56
	v_mul_f32_e32 v57, v61, v57
	v_mul_f32_e32 v58, v62, v58
	v_mul_f32_e32 v59, v63, v59
	v_mul_f32_e32 v48, v52, v48
	v_mul_f32_e32 v49, v53, v49
	v_mul_f32_e32 v50, v54, v50
	v_mul_f32_e32 v51, v55, v51
	v_cvt_pk_bf16_f32 v60, v56, v57
	v_cvt_pk_bf16_f32 v61, v58, v59
	v_cvt_pk_bf16_f32 v62, v48, v49
	v_cvt_pk_bf16_f32 v63, v50, v51
	s_nop 1
	v_permlane16_swap_b32_e32 v60, v62
	v_permlane16_swap_b32_e32 v61, v63
	global_store_dwordx4 v168, v[60:63], s[100:101]
	s_add_u32 s100, s100, 0x16000
	s_addc_u32 s101, s101, 0
	v_mul_f32_e32 v160, 0xbfb8aa3b, v36
	v_mul_f32_e32 v161, 0xbfb8aa3b, v37
	v_mul_f32_e32 v162, 0xbfb8aa3b, v38
	v_mul_f32_e32 v163, 0xbfb8aa3b, v39
	v_mul_f32_e32 v164, 0xbfb8aa3b, v44
	v_mul_f32_e32 v165, 0xbfb8aa3b, v45
	v_mul_f32_e32 v166, 0xbfb8aa3b, v46
	v_mul_f32_e32 v167, 0xbfb8aa3b, v47
	v_exp_f32_e32 v160, v160
	v_exp_f32_e32 v161, v161
	v_exp_f32_e32 v162, v162
	v_exp_f32_e32 v163, v163
	v_exp_f32_e32 v164, v164
	v_exp_f32_e32 v165, v165
	v_exp_f32_e32 v166, v166
	v_exp_f32_e32 v167, v167
	v_add_f32_e32 v160, 1.0, v160
	v_add_f32_e32 v161, 1.0, v161
	v_add_f32_e32 v162, 1.0, v162
	v_add_f32_e32 v163, 1.0, v163
	v_add_f32_e32 v164, 1.0, v164
	v_add_f32_e32 v165, 1.0, v165
	v_add_f32_e32 v166, 1.0, v166
	v_add_f32_e32 v167, 1.0, v167
	v_rcp_f32_e32 v160, v160
	v_rcp_f32_e32 v161, v161
	v_rcp_f32_e32 v162, v162
	v_rcp_f32_e32 v163, v163
	v_rcp_f32_e32 v164, v164
	v_rcp_f32_e32 v165, v165
	v_rcp_f32_e32 v166, v166
	v_rcp_f32_e32 v167, v167
	v_mul_f32_e32 v36, v36, v160
	v_mul_f32_e32 v37, v37, v161
	v_mul_f32_e32 v38, v38, v162
	v_mul_f32_e32 v39, v39, v163
	v_mul_f32_e32 v44, v44, v164
	v_mul_f32_e32 v45, v45, v165
	v_mul_f32_e32 v46, v46, v166
	v_mul_f32_e32 v47, v47, v167
	v_mul_f32_e32 v32, v36, v32
	v_mul_f32_e32 v33, v37, v33
	v_mul_f32_e32 v34, v38, v34
	v_mul_f32_e32 v35, v39, v35
	v_mul_f32_e32 v40, v44, v40
	v_mul_f32_e32 v41, v45, v41
	v_mul_f32_e32 v42, v46, v42
	v_mul_f32_e32 v43, v47, v43
	v_cvt_pk_bf16_f32 v36, v32, v33
	v_cvt_pk_bf16_f32 v37, v34, v35
	v_cvt_pk_bf16_f32 v38, v40, v41
	v_cvt_pk_bf16_f32 v39, v42, v43
	s_nop 1
	v_permlane16_swap_b32_e32 v36, v38
	v_permlane16_swap_b32_e32 v37, v39
	global_store_dwordx4 v168, v[36:39], s[100:101]
	s_and_b64 vcc, exec, s[16:17]
	s_mov_b32 s24, s20
	s_mov_b32 s22, s18
	s_mov_b64 s[26:27], s[12:13]
	s_mov_b64 s[4:5], s[10:11]
	s_cbranch_vccz .LBB0_1143

	.amdhsa_kernel _Z4mega1Pii
		.amdhsa_group_segment_fixed_size 147472
		.amdhsa_private_segment_fixed_size 0
		.amdhsa_kernarg_size 544
		.amdhsa_user_sgpr_count 2
		.amdhsa_user_sgpr_dispatch_ptr 0
		.amdhsa_user_sgpr_queue_ptr 0
		.amdhsa_user_sgpr_kernarg_segment_ptr 1
		.amdhsa_user_sgpr_dispatch_id 0
		.amdhsa_user_sgpr_kernarg_preload_length 0
		.amdhsa_user_sgpr_kernarg_preload_offset 0
		.amdhsa_user_sgpr_private_segment_size 0
		.amdhsa_uses_dynamic_stack 0
		.amdhsa_enable_private_segment 0
		.amdhsa_system_sgpr_workgroup_id_x 1
		.amdhsa_system_sgpr_workgroup_id_y 0
		.amdhsa_system_sgpr_workgroup_id_z 0
		.amdhsa_system_sgpr_workgroup_info 0
		.amdhsa_system_vgpr_workitem_id 2
		.amdhsa_next_free_vgpr 253
		.amdhsa_next_free_sgpr 102
		.amdhsa_accum_offset 256
		.amdhsa_reserve_vcc 1
		.amdhsa_float_round_mode_32 0
		.amdhsa_float_round_mode_16_64 0
		.amdhsa_float_denorm_mode_32 3
		.amdhsa_float_denorm_mode_16_64 3
		.amdhsa_dx10_clamp 1
		.amdhsa_ieee_mode 1
		.amdhsa_fp16_overflow 0
		.amdhsa_tg_split 0
		.amdhsa_exception_fp_ieee_invalid_op 0
		.amdhsa_exception_fp_denorm_src 0
		.amdhsa_exception_fp_ieee_div_zero 0
		.amdhsa_exception_fp_ieee_overflow 0
		.amdhsa_exception_fp_ieee_underflow 0
		.amdhsa_exception_fp_ieee_inexact 0
		.amdhsa_exception_int_div_zero 0
	.end_amdhsa_kernel

amdhsa.kernels:
  - .agpr_count:     0
    .args:
      - .offset:         0
        .size:           280
        .value_kind:     by_value
      - .offset:         280
        .size:           4
        .value_kind:     by_value
      - .offset:         284
        .size:           4
        .value_kind:     by_value
      - .offset:         288
        .size:           4
        .value_kind:     hidden_block_count_x
      - .offset:         292
        .size:           4
        .value_kind:     hidden_block_count_y
      - .offset:         296
        .size:           4
        .value_kind:     hidden_block_count_z
      - .offset:         300
        .size:           2
        .value_kind:     hidden_group_size_x
      - .offset:         302
        .size:           2
        .value_kind:     hidden_group_size_y
      - .offset:         304
        .size:           2
        .value_kind:     hidden_group_size_z
      - .offset:         306
        .size:           2
        .value_kind:     hidden_remainder_x
      - .offset:         308
        .size:           2
        .value_kind:     hidden_remainder_y
      - .offset:         310
        .size:           2
        .value_kind:     hidden_remainder_z
      - .offset:         328
        .size:           8
        .value_kind:     hidden_global_offset_x
      - .offset:         336
        .size:           8
        .value_kind:     hidden_global_offset_y
      - .offset:         344
        .size:           8
        .value_kind:     hidden_global_offset_z
      - .offset:         352
        .size:           2
        .value_kind:     hidden_grid_dims
      - .offset:         376
        .size:           8
        .value_kind:     hidden_multigrid_sync_arg
    .group_segment_fixed_size: 147472
    .kernarg_segment_align: 8
    .kernarg_segment_size: 544
    .language:       OpenCL C
    .language_version:
      - 2
      - 0
    .max_flat_workgroup_size: 512
    .name:           _Z4mega1Pii
    .private_segment_fixed_size: 0
    .sgpr_count:     108
    .sgpr_spill_count: 8
    .symbol:         _Z4mega1Pii.kd
    .uniform_work_group_size: 1
    .uses_dynamic_stack: false
    .vgpr_count:     253
    .vgpr_spill_count: 0
    .wavefront_size: 64
